# post_odd loop: per-trip vmcnt(0) at the top replaced by one wait before the loop (the latch vmcnt(2) already covers the prefetched rows)
# baseline (speedup 1.0000x reference)
.LBB0_361:
	s_or_b64 exec, exec, s[30:31]
	v_readlane_b32 s0, v251, 63
	v_readlane_b32 s1, v252, 0
	s_andn2_b64 vcc, exec, s[0:1]
	s_waitcnt vmcnt(0) lgkmcnt(0)
	s_barrier
	s_cbranch_vccnz .LBB0_384
	v_readlane_b32 s36, v251, 47
	v_lshlrev_b32_e32 v0, 3, v56
	v_ashrrev_i32_e32 v82, 6, v56
	v_readlane_b32 s24, v254, 34
	v_readlane_b32 s37, v251, 48
	v_and_b32_e32 v18, 56, v0
	v_readlane_b32 s4, v255, 26
	v_and_b32_e32 v20, 63, v56
	v_add_u32_e32 v19, s24, v82
	v_mov_b64_e32 v[16:17], s[36:37]
	s_movk_i32 s0, 0xc00
	v_lshlrev_b32_e32 v12, 2, v18
	v_readlane_b32 s16, v255, 38
	v_readlane_b32 s17, v255, 39
	v_mad_i64_i32 v[16:17], s[0:1], v19, s0, v[16:17]
	v_lshlrev_b32_e32 v96, 4, v20
	v_readlane_b32 s18, v255, 40
	v_readlane_b32 s19, v255, 41
	s_nop 0
	global_load_dwordx4 v[0:3], v12, s[16:17] offset:16
	s_nop 2
	global_load_dwordx4 v[4:7], v12, s[18:19] offset:16
	global_load_dwordx4 v[8:11], v12, s[16:17]
	s_nop 0
	global_load_dwordx4 v[12:15], v12, s[18:19]
	v_lshl_add_u64 v[16:17], v[16:17], 0, v[96:97]
	global_load_dwordx4 v[52:55], v[16:17], off
	global_load_dwordx4 v[48:51], v[16:17], off offset:1024
	global_load_dwordx4 v[44:47], v[16:17], off offset:2048
	v_and_b32_e32 v16, 4, v56
	v_cmp_eq_u32_e64 s[0:1], 0, v16
	v_lshlrev_b32_e32 v16, 6, v56
	v_and_b32_e32 v16, 64, v16
	v_and_b32_e32 v17, 64, v210
	v_add_u32_e32 v83, 0, v16
	v_xor_b32_e32 v16, 1, v210
	v_add_u32_e32 v17, 64, v17
	v_cmp_lt_i32_e32 vcc, v16, v17
	v_readlane_b32 s30, v251, 24
	v_readlane_b32 s31, v251, 25
	v_cndmask_b32_e32 v16, v210, v16, vcc
	v_lshlrev_b32_e32 v84, 2, v16
	v_xor_b32_e32 v16, 2, v210
	v_cmp_lt_i32_e32 vcc, v16, v17
	v_mov_b32_e32 v19, v97
	v_lshlrev_b32_e32 v21, 1, v82
	v_cndmask_b32_e32 v16, v210, v16, vcc
	v_lshlrev_b32_e32 v85, 2, v16
	v_xor_b32_e32 v16, 4, v210
	v_cmp_lt_i32_e32 vcc, v16, v17
	v_mov_b32_e32 v17, v97
	s_movk_i32 s3, 0x100
	v_cndmask_b32_e32 v16, v210, v16, vcc
	v_lshlrev_b32_e32 v86, 2, v16
	v_lshlrev_b32_e32 v16, 1, v18
	v_lshl_add_u64 v[58:59], s[30:31], 0, v[16:17]
	v_and_b32_e32 v18, 2, v56
	v_readlane_b32 s30, v251, 61
	v_cmp_eq_u32_e64 s[40:41], 0, v18
	v_lshlrev_b32_e32 v18, 5, v20
	v_readlane_b32 s31, v251, 62
	v_bfe_u32 v87, v56, 3, 3
	v_cmp_lt_u32_e64 s[44:45], 31, v20
	v_lshl_add_u64 v[62:63], s[30:31], 0, v[18:19]
	v_readlane_b32 s30, v251, 26
	v_readlane_b32 s31, v251, 27
	v_lshl_add_u64 v[60:61], s[90:91], 0, v[18:19]
	v_cmp_gt_u32_e64 s[46:47], 32, v20
	v_lshl_add_u64 v[64:65], s[30:31], 0, v[16:17]
	v_lshlrev_b32_e32 v17, 7, v20
	v_lshlrev_b32_e32 v16, 4, v56
	v_add3_u32 v17, 0, v21, v17
	v_cmp_gt_i32_e64 s[48:49], s3, v56
	v_ashrrev_i32_e32 v57, 31, v56
	v_add_u32_e32 v88, 0xfffff000, v17
	v_add_u32_e32 v89, 0xfffff010, v17
	v_add_u32_e32 v90, 0xfffff020, v17
	v_add_u32_e32 v91, 0xfffff030, v17
	v_add_u32_e32 v92, 0xfffff040, v17
	v_add_u32_e32 v93, 0xfffff050, v17
	v_add_u32_e32 v94, 0xfffff060, v17
	v_add_u32_e32 v95, 0xfffff070, v17
	v_lshl_add_u64 v[66:67], s[36:37], 0, v[96:97]
	v_add_u32_e32 v98, s77, v82
	v_add_u32_e32 v99, 0, v16
	s_mov_b32 s3, s24
	s_mov_b32 s24, s34
	v_readlane_b32 s5, v255, 27
	v_readlane_b32 s6, v255, 28
	v_readlane_b32 s7, v255, 29
	v_readlane_b32 s8, v255, 30
	v_readlane_b32 s9, v255, 31
	v_readlane_b32 s10, v255, 32
	v_readlane_b32 s11, v255, 33
	v_readlane_b32 s12, v255, 34
	v_readlane_b32 s13, v255, 35
	v_readlane_b32 s14, v255, 36
	v_readlane_b32 s15, v255, 37
	s_waitcnt vmcnt(0)
	s_branch .LBB0_364

.LBB0_366:
	s_or_b64 exec, exec, s[30:31]
	s_add_i32 s36, s24, s54
	s_cmpk_gt_i32 s36, 0xbff
	s_cselect_b64 s[30:31], -1, 0
	v_mov_b64_e32 v[24:25], v[44:45]
	v_mov_b64_e32 v[16:17], v[48:49]
	v_mov_b64_e32 v[20:21], v[52:53]
	s_and_b64 vcc, exec, s[30:31]
	v_mov_b64_e32 v[26:27], v[46:47]
	v_mov_b64_e32 v[18:19], v[50:51]
	v_mov_b64_e32 v[22:23], v[54:55]
	s_cbranch_vccnz .LBB0_368
	v_add_u32_e32 v16, s3, v98
	s_movk_i32 s37, 0xc00
	v_mad_i64_i32 v[24:25], s[42:43], v16, s37, v[66:67]
	global_load_dwordx4 v[20:23], v[24:25], off
	global_load_dwordx4 v[16:19], v[24:25], off offset:1024
	s_nop 0
	global_load_dwordx4 v[24:27], v[24:25], off offset:2048
